# Epi5 gated-accumulate epilogue: batched G/O loads (ring of 7 slots) instead of serialized load-wait-store
# speedup vs baseline: 1.0080x; 1.0080x over previous
; __device__ __forceinline__ float sigmoid_f(float x) { return __builtin_amdgcn_rcpf(1.f + __builtin_amdgcn_exp2f(-1.4426950408889634f * x)); }
; __device__ __forceinline__ float bf_lo(unsigned u) { return __uint_as_float(u << 16); }
; __device__ __forceinline__ float bf_hi(unsigned u) { return __uint_as_float(u & 0xffff0000u); }
; __device__ __forceinline__ u32x4 pack8(const f32x4 v0, const f32x4 v1) { u32x4 w; w.x = cvt_pk_bf16(v0[0], v0[1]); w.y = cvt_pk_bf16(v0[2], v0[3]); w.z = cvt_pk_bf16(v1[0], v1[1]); w.w = cvt_pk_bf16(v1[2], v1[3]); return w; }
;     __device__ __forceinline__ void operator()(const f32x4 (&acc)[2][2][4][2], const Unit& u, int wr, int wc, int fr, int fq) const {
;     ...
; #pragma unroll
;             for (int ai = 0; ai < 2; ++ai)
; #pragma unroll
;                 for (int m = 0; m < 4; ++m) { const int r = row0 + ai * HALF + m * 16;
;                     float sc = 1.f; if (MODE == 0 || MODE == 4) sc = __builtin_amdgcn_rsqf(row_ssq(ssq, r) * inv_n + RMS_EPS);
; #pragma unroll
;                     for (int bj = 0; bj < 2; ++bj) { f32x4 v0 = acc[ai][bj][m][0], v1 = acc[ai][bj][m][1]; bf16_t* p = ob + (unsigned)(r * ld + col0 + bj * HALF);
;                         if constexpr (MODE == 0) { v0 = v0 * sc; v1 = v1 * sc; }
;                         if constexpr (MODE == 3) { v0 = (v0 + bv[bj][0]) * sv[bj][0]; v1 = (v1 + bv[bj][1]) * sv[bj][1]; }
;                         if constexpr (MODE == 4) {
; #pragma unroll
;                             for (int e = 0; e < 4; ++e) { v0[e] = sigmoid_f(v0[e] * sc); v1[e] = sigmoid_f(v1[e] * sc); } }
;                         if constexpr (MODE == 5) { const u32x4 g = *(const u32x4*)(G + (unsigned)(r * ld + col0 + bj * HALF));
;                             v0 = v0 * (f32x4){bf_lo(g.x), bf_hi(g.x), bf_lo(g.y), bf_hi(g.y)}; v1 = v1 * (f32x4){bf_lo(g.z), bf_hi(g.z), bf_lo(g.w), bf_hi(g.w)};
;                             if (!first) { const u32x4 q = *(const u32x4*)p; v0 = v0 + (f32x4){bf_lo(q.x), bf_hi(q.x), bf_lo(q.y), bf_hi(q.y)}; v1 = v1 + (f32x4){bf_lo(q.z), bf_hi(q.z), bf_lo(q.w), bf_hi(q.w)}; } }
;                         *(u32x4*)p = pack8(v0, v1); }
;                     if (MODE == 5 || MODE == 4) asm volatile("" ::: "memory"); }
.LBB0_108:
	s_mov_b64 s[46:47], s[54:55]
	s_mov_b64 s[28:29], 0
	s_mov_b64 s[42:43], 0
	s_mov_b64 s[50:51], 0
	s_mov_b64 s[74:75], 0
	s_mov_b64 s[80:81], 0
	s_mov_b64 s[50:51], s[36:37]
	s_mov_b32 s74, 0
	s_mov_b32 s75, 0
	s_mov_b64 s[28:29], 0
	s_mov_b64 s[42:43], 0
	v_mov_b32_e32 v2, v184
	s_lshl_b32 s25, s25, 8
	s_add_i32 s25, s25, s77
	v_and_or_b32 v142, v2, 15, s25
	s_lshl_b32 s25, s91, 8
	v_lshrrev_b32_e32 v2, 1, v2
	v_and_or_b32 v2, v2, 24, s25
	v_or_b32_e32 v148, s88, v2
	v_lshlrev_b32_e32 v149, 10, v142
	v_add_u32_e32 v2, v148, v149
	v_lshlrev_b32_e32 v2, 1, v2
	s_andn2_b64 s[42:43], exec, s[44:45]
	s_and_b64 vcc, exec, s[44:45]
	s_cbranch_vccz .Le5_first
	s_add_u32 s98, s50, 0x0
	s_addc_u32 s99, s51, 0
	global_load_dwordx4 v[142:145], v2, s[98:99] offset:0
	s_add_u32 s100, s46, 0x0
	s_addc_u32 s101, s47, 0
	global_load_dwordx4 v[148:151], v2, s[100:101] offset:0
	s_add_u32 s98, s50, 0x0
	s_addc_u32 s99, s51, 0
	global_load_dwordx4 v[152:155], v2, s[98:99] offset:256
	s_add_u32 s100, s46, 0x0
	s_addc_u32 s101, s47, 0
	global_load_dwordx4 v[156:159], v2, s[100:101] offset:256
	s_add_u32 s98, s50, 0x8000
	s_addc_u32 s99, s51, 0
	global_load_dwordx4 v[160:163], v2, s[98:99] offset:0
	s_add_u32 s100, s46, 0x8000
	s_addc_u32 s101, s47, 0
	global_load_dwordx4 v[164:167], v2, s[100:101] offset:0
	s_add_u32 s98, s50, 0x8000
	s_addc_u32 s99, s51, 0
	global_load_dwordx4 v[168:171], v2, s[98:99] offset:256
	s_add_u32 s100, s46, 0x8000
	s_addc_u32 s101, s47, 0
	global_load_dwordx4 v[172:175], v2, s[100:101] offset:256
	s_add_u32 s98, s50, 0x10000
	s_addc_u32 s99, s51, 0
	global_load_dwordx4 v[176:179], v2, s[98:99] offset:0
	s_add_u32 s100, s46, 0x10000
	s_addc_u32 s101, s47, 0
	global_load_dwordx4 v[180:183], v2, s[100:101] offset:0
	s_add_u32 s98, s50, 0x10000
	s_addc_u32 s99, s51, 0
	global_load_dwordx4 v[194:197], v2, s[98:99] offset:256
	s_add_u32 s100, s46, 0x10000
	s_addc_u32 s101, s47, 0
	global_load_dwordx4 v[198:201], v2, s[100:101] offset:256
	s_add_u32 s98, s50, 0x18000
	s_addc_u32 s99, s51, 0
	global_load_dwordx4 v[202:205], v2, s[98:99] offset:0
	s_add_u32 s100, s46, 0x18000
	s_addc_u32 s101, s47, 0
	global_load_dwordx4 v[206:209], v2, s[100:101] offset:0
	s_waitcnt vmcnt(12)
	v_lshlrev_b32_e32 v220, 16, v142
	v_and_b32_e32 v221, 0xffff0000, v142
	v_pk_mul_f32 v[128:129], v[128:129], v[220:221]
	v_lshlrev_b32_e32 v222, 16, v143
	v_and_b32_e32 v223, 0xffff0000, v143
	v_pk_mul_f32 v[130:131], v[130:131], v[222:223]
	v_lshlrev_b32_e32 v224, 16, v144
	v_and_b32_e32 v225, 0xffff0000, v144
	v_pk_mul_f32 v[124:125], v[124:125], v[224:225]
	v_lshlrev_b32_e32 v226, 16, v145
	v_and_b32_e32 v227, 0xffff0000, v145
	v_pk_mul_f32 v[126:127], v[126:127], v[226:227]
	v_lshlrev_b32_e32 v220, 16, v148
	v_and_b32_e32 v221, 0xffff0000, v148
	v_pk_add_f32 v[128:129], v[128:129], v[220:221]
	v_lshlrev_b32_e32 v222, 16, v149
	v_and_b32_e32 v223, 0xffff0000, v149
	v_pk_add_f32 v[130:131], v[130:131], v[222:223]
	v_lshlrev_b32_e32 v224, 16, v150
	v_and_b32_e32 v225, 0xffff0000, v150
	v_pk_add_f32 v[124:125], v[124:125], v[224:225]
	v_lshlrev_b32_e32 v226, 16, v151
	v_and_b32_e32 v227, 0xffff0000, v151
	v_pk_add_f32 v[126:127], v[126:127], v[226:227]
	v_cvt_pk_bf16_f32 v128, v128, v129
	v_cvt_pk_bf16_f32 v129, v130, v131
	v_cvt_pk_bf16_f32 v130, v124, v125
	v_cvt_pk_bf16_f32 v131, v126, v127
	s_add_u32 s100, s46, 0x0
	s_addc_u32 s101, s47, 0
	global_store_dwordx4 v2, v[128:131], s[100:101] offset:0
	s_add_u32 s98, s50, 0x18000
	s_addc_u32 s99, s51, 0
	global_load_dwordx4 v[142:145], v2, s[98:99] offset:256
	s_add_u32 s100, s46, 0x18000
	s_addc_u32 s101, s47, 0
	global_load_dwordx4 v[148:151], v2, s[100:101] offset:256
	s_waitcnt vmcnt(13)
	v_lshlrev_b32_e32 v220, 16, v152
	v_and_b32_e32 v221, 0xffff0000, v152
	v_pk_mul_f32 v[120:121], v[120:121], v[220:221]
	v_lshlrev_b32_e32 v222, 16, v153
	v_and_b32_e32 v223, 0xffff0000, v153
	v_pk_mul_f32 v[122:123], v[122:123], v[222:223]
	v_lshlrev_b32_e32 v224, 16, v154
	v_and_b32_e32 v225, 0xffff0000, v154
	v_pk_mul_f32 v[116:117], v[116:117], v[224:225]
	v_lshlrev_b32_e32 v226, 16, v155
	v_and_b32_e32 v227, 0xffff0000, v155
	v_pk_mul_f32 v[118:119], v[118:119], v[226:227]
	v_lshlrev_b32_e32 v220, 16, v156
	v_and_b32_e32 v221, 0xffff0000, v156
	v_pk_add_f32 v[120:121], v[120:121], v[220:221]
	v_lshlrev_b32_e32 v222, 16, v157
	v_and_b32_e32 v223, 0xffff0000, v157
	v_pk_add_f32 v[122:123], v[122:123], v[222:223]
	v_lshlrev_b32_e32 v224, 16, v158
	v_and_b32_e32 v225, 0xffff0000, v158
	v_pk_add_f32 v[116:117], v[116:117], v[224:225]
	v_lshlrev_b32_e32 v226, 16, v159
	v_and_b32_e32 v227, 0xffff0000, v159
	v_pk_add_f32 v[118:119], v[118:119], v[226:227]
	v_cvt_pk_bf16_f32 v120, v120, v121
	v_cvt_pk_bf16_f32 v121, v122, v123
	v_cvt_pk_bf16_f32 v122, v116, v117
	v_cvt_pk_bf16_f32 v123, v118, v119
	s_add_u32 s100, s46, 0x0
	s_addc_u32 s101, s47, 0
	global_store_dwordx4 v2, v[120:123], s[100:101] offset:256
	s_add_u32 s98, s50, 0x40000
	s_addc_u32 s99, s51, 0
	global_load_dwordx4 v[152:155], v2, s[98:99] offset:0
	s_add_u32 s100, s46, 0x40000
	s_addc_u32 s101, s47, 0
	global_load_dwordx4 v[156:159], v2, s[100:101] offset:0
	s_waitcnt vmcnt(14)
; __device__ __forceinline__ float sigmoid_f(float x) { return __builtin_amdgcn_rcpf(1.f + __builtin_amdgcn_exp2f(-1.4426950408889634f * x)); }
; __device__ __forceinline__ float bf_lo(unsigned u) { return __uint_as_float(u << 16); }
; __device__ __forceinline__ float bf_hi(unsigned u) { return __uint_as_float(u & 0xffff0000u); }
; __device__ __forceinline__ u32x4 pack8(const f32x4 v0, const f32x4 v1) { u32x4 w; w.x = cvt_pk_bf16(v0[0], v0[1]); w.y = cvt_pk_bf16(v0[2], v0[3]); w.z = cvt_pk_bf16(v1[0], v1[1]); w.w = cvt_pk_bf16(v1[2], v1[3]); return w; }
;     __device__ __forceinline__ void operator()(const f32x4 (&acc)[2][2][4][2], const Unit& u, int wr, int wc, int fr, int fq) const {
;     ...
;                     for (int bj = 0; bj < 2; ++bj) { f32x4 v0 = acc[ai][bj][m][0], v1 = acc[ai][bj][m][1]; bf16_t* p = ob + (unsigned)(r * ld + col0 + bj * HALF);
;                         if constexpr (MODE == 0) { v0 = v0 * sc; v1 = v1 * sc; }
;                         if constexpr (MODE == 3) { v0 = (v0 + bv[bj][0]) * sv[bj][0]; v1 = (v1 + bv[bj][1]) * sv[bj][1]; }
;                         if constexpr (MODE == 4) {
; #pragma unroll
;                             for (int e = 0; e < 4; ++e) { v0[e] = sigmoid_f(v0[e] * sc); v1[e] = sigmoid_f(v1[e] * sc); } }
;                         if constexpr (MODE == 5) { const u32x4 g = *(const u32x4*)(G + (unsigned)(r * ld + col0 + bj * HALF));
;                             v0 = v0 * (f32x4){bf_lo(g.x), bf_hi(g.x), bf_lo(g.y), bf_hi(g.y)}; v1 = v1 * (f32x4){bf_lo(g.z), bf_hi(g.z), bf_lo(g.w), bf_hi(g.w)};
;                             if (!first) { const u32x4 q = *(const u32x4*)p; v0 = v0 + (f32x4){bf_lo(q.x), bf_hi(q.x), bf_lo(q.y), bf_hi(q.y)}; v1 = v1 + (f32x4){bf_lo(q.z), bf_hi(q.z), bf_lo(q.w), bf_hi(q.w)}; } }
;                         *(u32x4*)p = pack8(v0, v1); }
	v_lshlrev_b32_e32 v220, 16, v160
	v_and_b32_e32 v221, 0xffff0000, v160
	v_pk_mul_f32 v[112:113], v[112:113], v[220:221]
	v_lshlrev_b32_e32 v222, 16, v161
	v_and_b32_e32 v223, 0xffff0000, v161
	v_pk_mul_f32 v[114:115], v[114:115], v[222:223]
	v_lshlrev_b32_e32 v224, 16, v162
	v_and_b32_e32 v225, 0xffff0000, v162
	v_pk_mul_f32 v[108:109], v[108:109], v[224:225]
	v_lshlrev_b32_e32 v226, 16, v163
	v_and_b32_e32 v227, 0xffff0000, v163
	v_pk_mul_f32 v[110:111], v[110:111], v[226:227]
	v_lshlrev_b32_e32 v220, 16, v164
	v_and_b32_e32 v221, 0xffff0000, v164
	v_pk_add_f32 v[112:113], v[112:113], v[220:221]
	v_lshlrev_b32_e32 v222, 16, v165
	v_and_b32_e32 v223, 0xffff0000, v165
	v_pk_add_f32 v[114:115], v[114:115], v[222:223]
	v_lshlrev_b32_e32 v224, 16, v166
	v_and_b32_e32 v225, 0xffff0000, v166
	v_pk_add_f32 v[108:109], v[108:109], v[224:225]
	v_lshlrev_b32_e32 v226, 16, v167
	v_and_b32_e32 v227, 0xffff0000, v167
	v_pk_add_f32 v[110:111], v[110:111], v[226:227]
	v_cvt_pk_bf16_f32 v112, v112, v113
	v_cvt_pk_bf16_f32 v113, v114, v115
	v_cvt_pk_bf16_f32 v114, v108, v109
	v_cvt_pk_bf16_f32 v115, v110, v111
	s_add_u32 s100, s46, 0x8000
	s_addc_u32 s101, s47, 0
	global_store_dwordx4 v2, v[112:115], s[100:101] offset:0
	s_add_u32 s98, s50, 0x40000
	s_addc_u32 s99, s51, 0
	global_load_dwordx4 v[160:163], v2, s[98:99] offset:256
	s_add_u32 s100, s46, 0x40000
	s_addc_u32 s101, s47, 0
	global_load_dwordx4 v[164:167], v2, s[100:101] offset:256
	s_waitcnt vmcnt(15)
	v_lshlrev_b32_e32 v220, 16, v168
	v_and_b32_e32 v221, 0xffff0000, v168
	v_pk_mul_f32 v[104:105], v[104:105], v[220:221]
	v_lshlrev_b32_e32 v222, 16, v169
	v_and_b32_e32 v223, 0xffff0000, v169
	v_pk_mul_f32 v[106:107], v[106:107], v[222:223]
	v_lshlrev_b32_e32 v224, 16, v170
	v_and_b32_e32 v225, 0xffff0000, v170
	v_pk_mul_f32 v[100:101], v[100:101], v[224:225]
	v_lshlrev_b32_e32 v226, 16, v171
	v_and_b32_e32 v227, 0xffff0000, v171
	v_pk_mul_f32 v[102:103], v[102:103], v[226:227]
	v_lshlrev_b32_e32 v220, 16, v172
	v_and_b32_e32 v221, 0xffff0000, v172
	v_pk_add_f32 v[104:105], v[104:105], v[220:221]
	v_lshlrev_b32_e32 v222, 16, v173
	v_and_b32_e32 v223, 0xffff0000, v173
	v_pk_add_f32 v[106:107], v[106:107], v[222:223]
	v_lshlrev_b32_e32 v224, 16, v174
	v_and_b32_e32 v225, 0xffff0000, v174
	v_pk_add_f32 v[100:101], v[100:101], v[224:225]
	v_lshlrev_b32_e32 v226, 16, v175
	v_and_b32_e32 v227, 0xffff0000, v175
	v_pk_add_f32 v[102:103], v[102:103], v[226:227]
	v_cvt_pk_bf16_f32 v104, v104, v105
	v_cvt_pk_bf16_f32 v105, v106, v107
	v_cvt_pk_bf16_f32 v106, v100, v101
	v_cvt_pk_bf16_f32 v107, v102, v103
	s_add_u32 s100, s46, 0x8000
	s_addc_u32 s101, s47, 0
	global_store_dwordx4 v2, v[104:107], s[100:101] offset:256
	s_add_u32 s98, s50, 0x48000
	s_addc_u32 s99, s51, 0
	global_load_dwordx4 v[168:171], v2, s[98:99] offset:0
	s_add_u32 s100, s46, 0x48000
	s_addc_u32 s101, s47, 0
	global_load_dwordx4 v[172:175], v2, s[100:101] offset:0
	s_waitcnt vmcnt(16)
	v_lshlrev_b32_e32 v220, 16, v176
	v_and_b32_e32 v221, 0xffff0000, v176
	v_pk_mul_f32 v[96:97], v[96:97], v[220:221]
	v_lshlrev_b32_e32 v222, 16, v177
	v_and_b32_e32 v223, 0xffff0000, v177
	v_pk_mul_f32 v[98:99], v[98:99], v[222:223]
	v_lshlrev_b32_e32 v224, 16, v178
	v_and_b32_e32 v225, 0xffff0000, v178
	v_pk_mul_f32 v[92:93], v[92:93], v[224:225]
	v_lshlrev_b32_e32 v226, 16, v179
	v_and_b32_e32 v227, 0xffff0000, v179
	v_pk_mul_f32 v[94:95], v[94:95], v[226:227]
	v_lshlrev_b32_e32 v220, 16, v180
	v_and_b32_e32 v221, 0xffff0000, v180
	v_pk_add_f32 v[96:97], v[96:97], v[220:221]
	v_lshlrev_b32_e32 v222, 16, v181
	v_and_b32_e32 v223, 0xffff0000, v181
	v_pk_add_f32 v[98:99], v[98:99], v[222:223]
	v_lshlrev_b32_e32 v224, 16, v182
	v_and_b32_e32 v225, 0xffff0000, v182
	v_pk_add_f32 v[92:93], v[92:93], v[224:225]
	v_lshlrev_b32_e32 v226, 16, v183
	v_and_b32_e32 v227, 0xffff0000, v183
	v_pk_add_f32 v[94:95], v[94:95], v[226:227]
	v_cvt_pk_bf16_f32 v96, v96, v97
	v_cvt_pk_bf16_f32 v97, v98, v99
	v_cvt_pk_bf16_f32 v98, v92, v93
	v_cvt_pk_bf16_f32 v99, v94, v95
	s_add_u32 s100, s46, 0x10000
	s_addc_u32 s101, s47, 0
	global_store_dwordx4 v2, v[96:99], s[100:101] offset:0
	s_add_u32 s98, s50, 0x48000
	s_addc_u32 s99, s51, 0
	global_load_dwordx4 v[176:179], v2, s[98:99] offset:256
	s_add_u32 s100, s46, 0x48000
	s_addc_u32 s101, s47, 0
	global_load_dwordx4 v[180:183], v2, s[100:101] offset:256
	s_waitcnt vmcnt(17)
	v_lshlrev_b32_e32 v220, 16, v194
	v_and_b32_e32 v221, 0xffff0000, v194
	v_pk_mul_f32 v[88:89], v[88:89], v[220:221]
	v_lshlrev_b32_e32 v222, 16, v195
	v_and_b32_e32 v223, 0xffff0000, v195
	v_pk_mul_f32 v[90:91], v[90:91], v[222:223]
	v_lshlrev_b32_e32 v224, 16, v196
	v_and_b32_e32 v225, 0xffff0000, v196
	v_pk_mul_f32 v[84:85], v[84:85], v[224:225]
	v_lshlrev_b32_e32 v226, 16, v197
	v_and_b32_e32 v227, 0xffff0000, v197
	v_pk_mul_f32 v[86:87], v[86:87], v[226:227]
	v_lshlrev_b32_e32 v220, 16, v198
	v_and_b32_e32 v221, 0xffff0000, v198
	v_pk_add_f32 v[88:89], v[88:89], v[220:221]
	v_lshlrev_b32_e32 v222, 16, v199
	v_and_b32_e32 v223, 0xffff0000, v199
	v_pk_add_f32 v[90:91], v[90:91], v[222:223]
	v_lshlrev_b32_e32 v224, 16, v200
	v_and_b32_e32 v225, 0xffff0000, v200
	v_pk_add_f32 v[84:85], v[84:85], v[224:225]
	v_lshlrev_b32_e32 v226, 16, v201
	v_and_b32_e32 v227, 0xffff0000, v201
	v_pk_add_f32 v[86:87], v[86:87], v[226:227]
	v_cvt_pk_bf16_f32 v88, v88, v89
	v_cvt_pk_bf16_f32 v89, v90, v91
	v_cvt_pk_bf16_f32 v90, v84, v85
	v_cvt_pk_bf16_f32 v91, v86, v87
	s_add_u32 s100, s46, 0x10000
	s_addc_u32 s101, s47, 0
	global_store_dwordx4 v2, v[88:91], s[100:101] offset:256
	s_add_u32 s98, s50, 0x50000
	s_addc_u32 s99, s51, 0
	global_load_dwordx4 v[194:197], v2, s[98:99] offset:0
	s_add_u32 s100, s46, 0x50000
	s_addc_u32 s101, s47, 0
	global_load_dwordx4 v[198:201], v2, s[100:101] offset:0
	s_waitcnt vmcnt(18)
; __device__ __forceinline__ float sigmoid_f(float x) { return __builtin_amdgcn_rcpf(1.f + __builtin_amdgcn_exp2f(-1.4426950408889634f * x)); }
; __device__ __forceinline__ float bf_lo(unsigned u) { return __uint_as_float(u << 16); }
; __device__ __forceinline__ float bf_hi(unsigned u) { return __uint_as_float(u & 0xffff0000u); }
; __device__ __forceinline__ u32x4 pack8(const f32x4 v0, const f32x4 v1) { u32x4 w; w.x = cvt_pk_bf16(v0[0], v0[1]); w.y = cvt_pk_bf16(v0[2], v0[3]); w.z = cvt_pk_bf16(v1[0], v1[1]); w.w = cvt_pk_bf16(v1[2], v1[3]); return w; }
;     __device__ __forceinline__ void operator()(const f32x4 (&acc)[2][2][4][2], const Unit& u, int wr, int wc, int fr, int fq) const {
;     ...
;                     for (int bj = 0; bj < 2; ++bj) { f32x4 v0 = acc[ai][bj][m][0], v1 = acc[ai][bj][m][1]; bf16_t* p = ob + (unsigned)(r * ld + col0 + bj * HALF);
;                         if constexpr (MODE == 0) { v0 = v0 * sc; v1 = v1 * sc; }
;                         if constexpr (MODE == 3) { v0 = (v0 + bv[bj][0]) * sv[bj][0]; v1 = (v1 + bv[bj][1]) * sv[bj][1]; }
;                         if constexpr (MODE == 4) {
; #pragma unroll
;                             for (int e = 0; e < 4; ++e) { v0[e] = sigmoid_f(v0[e] * sc); v1[e] = sigmoid_f(v1[e] * sc); } }
;                         if constexpr (MODE == 5) { const u32x4 g = *(const u32x4*)(G + (unsigned)(r * ld + col0 + bj * HALF));
;                             v0 = v0 * (f32x4){bf_lo(g.x), bf_hi(g.x), bf_lo(g.y), bf_hi(g.y)}; v1 = v1 * (f32x4){bf_lo(g.z), bf_hi(g.z), bf_lo(g.w), bf_hi(g.w)};
;                             if (!first) { const u32x4 q = *(const u32x4*)p; v0 = v0 + (f32x4){bf_lo(q.x), bf_hi(q.x), bf_lo(q.y), bf_hi(q.y)}; v1 = v1 + (f32x4){bf_lo(q.z), bf_hi(q.z), bf_lo(q.w), bf_hi(q.w)}; } }
;                         *(u32x4*)p = pack8(v0, v1); }
	v_lshlrev_b32_e32 v220, 16, v202
	v_and_b32_e32 v221, 0xffff0000, v202
	v_pk_mul_f32 v[80:81], v[80:81], v[220:221]
	v_lshlrev_b32_e32 v222, 16, v203
	v_and_b32_e32 v223, 0xffff0000, v203
	v_pk_mul_f32 v[82:83], v[82:83], v[222:223]
	v_lshlrev_b32_e32 v224, 16, v204
	v_and_b32_e32 v225, 0xffff0000, v204
	v_pk_mul_f32 v[76:77], v[76:77], v[224:225]
	v_lshlrev_b32_e32 v226, 16, v205
	v_and_b32_e32 v227, 0xffff0000, v205
	v_pk_mul_f32 v[78:79], v[78:79], v[226:227]
	v_lshlrev_b32_e32 v220, 16, v206
	v_and_b32_e32 v221, 0xffff0000, v206
	v_pk_add_f32 v[80:81], v[80:81], v[220:221]
	v_lshlrev_b32_e32 v222, 16, v207
	v_and_b32_e32 v223, 0xffff0000, v207
	v_pk_add_f32 v[82:83], v[82:83], v[222:223]
	v_lshlrev_b32_e32 v224, 16, v208
	v_and_b32_e32 v225, 0xffff0000, v208
	v_pk_add_f32 v[76:77], v[76:77], v[224:225]
	v_lshlrev_b32_e32 v226, 16, v209
	v_and_b32_e32 v227, 0xffff0000, v209
	v_pk_add_f32 v[78:79], v[78:79], v[226:227]
	v_cvt_pk_bf16_f32 v80, v80, v81
	v_cvt_pk_bf16_f32 v81, v82, v83
	v_cvt_pk_bf16_f32 v82, v76, v77
	v_cvt_pk_bf16_f32 v83, v78, v79
	s_add_u32 s100, s46, 0x18000
	s_addc_u32 s101, s47, 0
	global_store_dwordx4 v2, v[80:83], s[100:101] offset:0
	s_add_u32 s98, s50, 0x50000
	s_addc_u32 s99, s51, 0
	global_load_dwordx4 v[202:205], v2, s[98:99] offset:256
	s_add_u32 s100, s46, 0x50000
	s_addc_u32 s101, s47, 0
	global_load_dwordx4 v[206:209], v2, s[100:101] offset:256
	s_waitcnt vmcnt(18)
	v_lshlrev_b32_e32 v220, 16, v142
	v_and_b32_e32 v221, 0xffff0000, v142
	v_pk_mul_f32 v[72:73], v[72:73], v[220:221]
	v_lshlrev_b32_e32 v222, 16, v143
	v_and_b32_e32 v223, 0xffff0000, v143
	v_pk_mul_f32 v[74:75], v[74:75], v[222:223]
	v_lshlrev_b32_e32 v224, 16, v144
	v_and_b32_e32 v225, 0xffff0000, v144
	v_pk_mul_f32 v[68:69], v[68:69], v[224:225]
	v_lshlrev_b32_e32 v226, 16, v145
	v_and_b32_e32 v227, 0xffff0000, v145
	v_pk_mul_f32 v[70:71], v[70:71], v[226:227]
	v_lshlrev_b32_e32 v220, 16, v148
	v_and_b32_e32 v221, 0xffff0000, v148
	v_pk_add_f32 v[72:73], v[72:73], v[220:221]
	v_lshlrev_b32_e32 v222, 16, v149
	v_and_b32_e32 v223, 0xffff0000, v149
	v_pk_add_f32 v[74:75], v[74:75], v[222:223]
	v_lshlrev_b32_e32 v224, 16, v150
	v_and_b32_e32 v225, 0xffff0000, v150
	v_pk_add_f32 v[68:69], v[68:69], v[224:225]
	v_lshlrev_b32_e32 v226, 16, v151
	v_and_b32_e32 v227, 0xffff0000, v151
	v_pk_add_f32 v[70:71], v[70:71], v[226:227]
	v_cvt_pk_bf16_f32 v72, v72, v73
	v_cvt_pk_bf16_f32 v73, v74, v75
	v_cvt_pk_bf16_f32 v74, v68, v69
	v_cvt_pk_bf16_f32 v75, v70, v71
	s_add_u32 s100, s46, 0x18000
	s_addc_u32 s101, s47, 0
	global_store_dwordx4 v2, v[72:75], s[100:101] offset:256
	s_add_u32 s98, s50, 0x58000
	s_addc_u32 s99, s51, 0
	global_load_dwordx4 v[142:145], v2, s[98:99] offset:0
	s_add_u32 s100, s46, 0x58000
	s_addc_u32 s101, s47, 0
	global_load_dwordx4 v[148:151], v2, s[100:101] offset:0
	s_waitcnt vmcnt(18)
	v_lshlrev_b32_e32 v220, 16, v152
	v_and_b32_e32 v221, 0xffff0000, v152
	v_pk_mul_f32 v[64:65], v[64:65], v[220:221]
	v_lshlrev_b32_e32 v222, 16, v153
	v_and_b32_e32 v223, 0xffff0000, v153
	v_pk_mul_f32 v[66:67], v[66:67], v[222:223]
	v_lshlrev_b32_e32 v224, 16, v154
	v_and_b32_e32 v225, 0xffff0000, v154
	v_pk_mul_f32 v[60:61], v[60:61], v[224:225]
	v_lshlrev_b32_e32 v226, 16, v155
	v_and_b32_e32 v227, 0xffff0000, v155
	v_pk_mul_f32 v[62:63], v[62:63], v[226:227]
	v_lshlrev_b32_e32 v220, 16, v156
	v_and_b32_e32 v221, 0xffff0000, v156
	v_pk_add_f32 v[64:65], v[64:65], v[220:221]
	v_lshlrev_b32_e32 v222, 16, v157
	v_and_b32_e32 v223, 0xffff0000, v157
	v_pk_add_f32 v[66:67], v[66:67], v[222:223]
	v_lshlrev_b32_e32 v224, 16, v158
	v_and_b32_e32 v225, 0xffff0000, v158
	v_pk_add_f32 v[60:61], v[60:61], v[224:225]
	v_lshlrev_b32_e32 v226, 16, v159
	v_and_b32_e32 v227, 0xffff0000, v159
	v_pk_add_f32 v[62:63], v[62:63], v[226:227]
	v_cvt_pk_bf16_f32 v64, v64, v65
	v_cvt_pk_bf16_f32 v65, v66, v67
	v_cvt_pk_bf16_f32 v66, v60, v61
	v_cvt_pk_bf16_f32 v67, v62, v63
	s_add_u32 s100, s46, 0x40000
	s_addc_u32 s101, s47, 0
	global_store_dwordx4 v2, v[64:67], s[100:101] offset:0
	s_add_u32 s98, s50, 0x58000
	s_addc_u32 s99, s51, 0
	global_load_dwordx4 v[152:155], v2, s[98:99] offset:256
	s_add_u32 s100, s46, 0x58000
	s_addc_u32 s101, s47, 0
	global_load_dwordx4 v[156:159], v2, s[100:101] offset:256
	s_waitcnt vmcnt(18)
	v_lshlrev_b32_e32 v220, 16, v160
	v_and_b32_e32 v221, 0xffff0000, v160
	v_pk_mul_f32 v[56:57], v[56:57], v[220:221]
	v_lshlrev_b32_e32 v222, 16, v161
	v_and_b32_e32 v223, 0xffff0000, v161
	v_pk_mul_f32 v[58:59], v[58:59], v[222:223]
	v_lshlrev_b32_e32 v224, 16, v162
	v_and_b32_e32 v225, 0xffff0000, v162
	v_pk_mul_f32 v[52:53], v[52:53], v[224:225]
	v_lshlrev_b32_e32 v226, 16, v163
	v_and_b32_e32 v227, 0xffff0000, v163
	v_pk_mul_f32 v[54:55], v[54:55], v[226:227]
	v_lshlrev_b32_e32 v220, 16, v164
	v_and_b32_e32 v221, 0xffff0000, v164
	v_pk_add_f32 v[56:57], v[56:57], v[220:221]
	v_lshlrev_b32_e32 v222, 16, v165
	v_and_b32_e32 v223, 0xffff0000, v165
	v_pk_add_f32 v[58:59], v[58:59], v[222:223]
	v_lshlrev_b32_e32 v224, 16, v166
	v_and_b32_e32 v225, 0xffff0000, v166
	v_pk_add_f32 v[52:53], v[52:53], v[224:225]
	v_lshlrev_b32_e32 v226, 16, v167
	v_and_b32_e32 v227, 0xffff0000, v167
	v_pk_add_f32 v[54:55], v[54:55], v[226:227]
	v_cvt_pk_bf16_f32 v56, v56, v57
	v_cvt_pk_bf16_f32 v57, v58, v59
	v_cvt_pk_bf16_f32 v58, v52, v53
	v_cvt_pk_bf16_f32 v59, v54, v55
	s_add_u32 s100, s46, 0x40000
	s_addc_u32 s101, s47, 0
	global_store_dwordx4 v2, v[56:59], s[100:101] offset:256
	s_waitcnt vmcnt(16)
; __device__ __forceinline__ float sigmoid_f(float x) { return __builtin_amdgcn_rcpf(1.f + __builtin_amdgcn_exp2f(-1.4426950408889634f * x)); }
; __device__ __forceinline__ float bf_lo(unsigned u) { return __uint_as_float(u << 16); }
; __device__ __forceinline__ float bf_hi(unsigned u) { return __uint_as_float(u & 0xffff0000u); }
; __device__ __forceinline__ u32x4 pack8(const f32x4 v0, const f32x4 v1) { u32x4 w; w.x = cvt_pk_bf16(v0[0], v0[1]); w.y = cvt_pk_bf16(v0[2], v0[3]); w.z = cvt_pk_bf16(v1[0], v1[1]); w.w = cvt_pk_bf16(v1[2], v1[3]); return w; }
;     __device__ __forceinline__ void operator()(const f32x4 (&acc)[2][2][4][2], const Unit& u, int wr, int wc, int fr, int fq) const {
;     ...
;                     for (int bj = 0; bj < 2; ++bj) { f32x4 v0 = acc[ai][bj][m][0], v1 = acc[ai][bj][m][1]; bf16_t* p = ob + (unsigned)(r * ld + col0 + bj * HALF);
;                         if constexpr (MODE == 0) { v0 = v0 * sc; v1 = v1 * sc; }
;                         if constexpr (MODE == 3) { v0 = (v0 + bv[bj][0]) * sv[bj][0]; v1 = (v1 + bv[bj][1]) * sv[bj][1]; }
;                         if constexpr (MODE == 4) {
; #pragma unroll
;                             for (int e = 0; e < 4; ++e) { v0[e] = sigmoid_f(v0[e] * sc); v1[e] = sigmoid_f(v1[e] * sc); } }
;                         if constexpr (MODE == 5) { const u32x4 g = *(const u32x4*)(G + (unsigned)(r * ld + col0 + bj * HALF));
;                             v0 = v0 * (f32x4){bf_lo(g.x), bf_hi(g.x), bf_lo(g.y), bf_hi(g.y)}; v1 = v1 * (f32x4){bf_lo(g.z), bf_hi(g.z), bf_lo(g.w), bf_hi(g.w)};
;                             if (!first) { const u32x4 q = *(const u32x4*)p; v0 = v0 + (f32x4){bf_lo(q.x), bf_hi(q.x), bf_lo(q.y), bf_hi(q.y)}; v1 = v1 + (f32x4){bf_lo(q.z), bf_hi(q.z), bf_lo(q.w), bf_hi(q.w)}; } }
;                         *(u32x4*)p = pack8(v0, v1); }
	v_lshlrev_b32_e32 v220, 16, v168
	v_and_b32_e32 v221, 0xffff0000, v168
	v_pk_mul_f32 v[48:49], v[48:49], v[220:221]
	v_lshlrev_b32_e32 v222, 16, v169
	v_and_b32_e32 v223, 0xffff0000, v169
	v_pk_mul_f32 v[50:51], v[50:51], v[222:223]
	v_lshlrev_b32_e32 v224, 16, v170
	v_and_b32_e32 v225, 0xffff0000, v170
	v_pk_mul_f32 v[44:45], v[44:45], v[224:225]
	v_lshlrev_b32_e32 v226, 16, v171
	v_and_b32_e32 v227, 0xffff0000, v171
	v_pk_mul_f32 v[46:47], v[46:47], v[226:227]
	v_lshlrev_b32_e32 v220, 16, v172
	v_and_b32_e32 v221, 0xffff0000, v172
	v_pk_add_f32 v[48:49], v[48:49], v[220:221]
	v_lshlrev_b32_e32 v222, 16, v173
	v_and_b32_e32 v223, 0xffff0000, v173
	v_pk_add_f32 v[50:51], v[50:51], v[222:223]
	v_lshlrev_b32_e32 v224, 16, v174
	v_and_b32_e32 v225, 0xffff0000, v174
	v_pk_add_f32 v[44:45], v[44:45], v[224:225]
	v_lshlrev_b32_e32 v226, 16, v175
	v_and_b32_e32 v227, 0xffff0000, v175
	v_pk_add_f32 v[46:47], v[46:47], v[226:227]
	v_cvt_pk_bf16_f32 v48, v48, v49
	v_cvt_pk_bf16_f32 v49, v50, v51
	v_cvt_pk_bf16_f32 v50, v44, v45
	v_cvt_pk_bf16_f32 v51, v46, v47
	s_add_u32 s100, s46, 0x48000
	s_addc_u32 s101, s47, 0
	global_store_dwordx4 v2, v[48:51], s[100:101] offset:0
	s_waitcnt vmcnt(14)
	v_lshlrev_b32_e32 v220, 16, v176
	v_and_b32_e32 v221, 0xffff0000, v176
	v_pk_mul_f32 v[40:41], v[40:41], v[220:221]
	v_lshlrev_b32_e32 v222, 16, v177
	v_and_b32_e32 v223, 0xffff0000, v177
	v_pk_mul_f32 v[42:43], v[42:43], v[222:223]
	v_lshlrev_b32_e32 v224, 16, v178
	v_and_b32_e32 v225, 0xffff0000, v178
	v_pk_mul_f32 v[36:37], v[36:37], v[224:225]
	v_lshlrev_b32_e32 v226, 16, v179
	v_and_b32_e32 v227, 0xffff0000, v179
	v_pk_mul_f32 v[38:39], v[38:39], v[226:227]
	v_lshlrev_b32_e32 v220, 16, v180
	v_and_b32_e32 v221, 0xffff0000, v180
	v_pk_add_f32 v[40:41], v[40:41], v[220:221]
	v_lshlrev_b32_e32 v222, 16, v181
	v_and_b32_e32 v223, 0xffff0000, v181
	v_pk_add_f32 v[42:43], v[42:43], v[222:223]
	v_lshlrev_b32_e32 v224, 16, v182
	v_and_b32_e32 v225, 0xffff0000, v182
	v_pk_add_f32 v[36:37], v[36:37], v[224:225]
	v_lshlrev_b32_e32 v226, 16, v183
	v_and_b32_e32 v227, 0xffff0000, v183
	v_pk_add_f32 v[38:39], v[38:39], v[226:227]
	v_cvt_pk_bf16_f32 v40, v40, v41
	v_cvt_pk_bf16_f32 v41, v42, v43
	v_cvt_pk_bf16_f32 v42, v36, v37
	v_cvt_pk_bf16_f32 v43, v38, v39
	s_add_u32 s100, s46, 0x48000
	s_addc_u32 s101, s47, 0
	global_store_dwordx4 v2, v[40:43], s[100:101] offset:256
	s_waitcnt vmcnt(12)
	v_lshlrev_b32_e32 v220, 16, v194
	v_and_b32_e32 v221, 0xffff0000, v194
	v_pk_mul_f32 v[32:33], v[32:33], v[220:221]
	v_lshlrev_b32_e32 v222, 16, v195
	v_and_b32_e32 v223, 0xffff0000, v195
	v_pk_mul_f32 v[34:35], v[34:35], v[222:223]
	v_lshlrev_b32_e32 v224, 16, v196
	v_and_b32_e32 v225, 0xffff0000, v196
	v_pk_mul_f32 v[28:29], v[28:29], v[224:225]
	v_lshlrev_b32_e32 v226, 16, v197
	v_and_b32_e32 v227, 0xffff0000, v197
	v_pk_mul_f32 v[30:31], v[30:31], v[226:227]
	v_lshlrev_b32_e32 v220, 16, v198
	v_and_b32_e32 v221, 0xffff0000, v198
	v_pk_add_f32 v[32:33], v[32:33], v[220:221]
	v_lshlrev_b32_e32 v222, 16, v199
	v_and_b32_e32 v223, 0xffff0000, v199
	v_pk_add_f32 v[34:35], v[34:35], v[222:223]
	v_lshlrev_b32_e32 v224, 16, v200
	v_and_b32_e32 v225, 0xffff0000, v200
	v_pk_add_f32 v[28:29], v[28:29], v[224:225]
	v_lshlrev_b32_e32 v226, 16, v201
	v_and_b32_e32 v227, 0xffff0000, v201
	v_pk_add_f32 v[30:31], v[30:31], v[226:227]
	v_cvt_pk_bf16_f32 v32, v32, v33
	v_cvt_pk_bf16_f32 v33, v34, v35
	v_cvt_pk_bf16_f32 v34, v28, v29
	v_cvt_pk_bf16_f32 v35, v30, v31
	s_add_u32 s100, s46, 0x50000
	s_addc_u32 s101, s47, 0
	global_store_dwordx4 v2, v[32:35], s[100:101] offset:0
	s_waitcnt vmcnt(10)
	v_lshlrev_b32_e32 v220, 16, v202
	v_and_b32_e32 v221, 0xffff0000, v202
	v_pk_mul_f32 v[24:25], v[24:25], v[220:221]
	v_lshlrev_b32_e32 v222, 16, v203
	v_and_b32_e32 v223, 0xffff0000, v203
	v_pk_mul_f32 v[26:27], v[26:27], v[222:223]
	v_lshlrev_b32_e32 v224, 16, v204
	v_and_b32_e32 v225, 0xffff0000, v204
	v_pk_mul_f32 v[20:21], v[20:21], v[224:225]
	v_lshlrev_b32_e32 v226, 16, v205
	v_and_b32_e32 v227, 0xffff0000, v205
	v_pk_mul_f32 v[22:23], v[22:23], v[226:227]
	v_lshlrev_b32_e32 v220, 16, v206
	v_and_b32_e32 v221, 0xffff0000, v206
	v_pk_add_f32 v[24:25], v[24:25], v[220:221]
	v_lshlrev_b32_e32 v222, 16, v207
	v_and_b32_e32 v223, 0xffff0000, v207
	v_pk_add_f32 v[26:27], v[26:27], v[222:223]
	v_lshlrev_b32_e32 v224, 16, v208
	v_and_b32_e32 v225, 0xffff0000, v208
	v_pk_add_f32 v[20:21], v[20:21], v[224:225]
	v_lshlrev_b32_e32 v226, 16, v209
	v_and_b32_e32 v227, 0xffff0000, v209
	v_pk_add_f32 v[22:23], v[22:23], v[226:227]
	v_cvt_pk_bf16_f32 v24, v24, v25
	v_cvt_pk_bf16_f32 v25, v26, v27
	v_cvt_pk_bf16_f32 v26, v20, v21
	v_cvt_pk_bf16_f32 v27, v22, v23
	s_add_u32 s100, s46, 0x50000
	s_addc_u32 s101, s47, 0
	global_store_dwordx4 v2, v[24:27], s[100:101] offset:256
	s_waitcnt vmcnt(8)
	v_lshlrev_b32_e32 v220, 16, v142
	v_and_b32_e32 v221, 0xffff0000, v142
	v_pk_mul_f32 v[16:17], v[16:17], v[220:221]
	v_lshlrev_b32_e32 v222, 16, v143
	v_and_b32_e32 v223, 0xffff0000, v143
	v_pk_mul_f32 v[18:19], v[18:19], v[222:223]
	v_lshlrev_b32_e32 v224, 16, v144
	v_and_b32_e32 v225, 0xffff0000, v144
	v_pk_mul_f32 v[12:13], v[12:13], v[224:225]
	v_lshlrev_b32_e32 v226, 16, v145
	v_and_b32_e32 v227, 0xffff0000, v145
	v_pk_mul_f32 v[14:15], v[14:15], v[226:227]
	v_lshlrev_b32_e32 v220, 16, v148
	v_and_b32_e32 v221, 0xffff0000, v148
	v_pk_add_f32 v[16:17], v[16:17], v[220:221]
	v_lshlrev_b32_e32 v222, 16, v149
	v_and_b32_e32 v223, 0xffff0000, v149
	v_pk_add_f32 v[18:19], v[18:19], v[222:223]
	v_lshlrev_b32_e32 v224, 16, v150
	v_and_b32_e32 v225, 0xffff0000, v150
	v_pk_add_f32 v[12:13], v[12:13], v[224:225]
	v_lshlrev_b32_e32 v226, 16, v151
	v_and_b32_e32 v227, 0xffff0000, v151
	v_pk_add_f32 v[14:15], v[14:15], v[226:227]
	v_cvt_pk_bf16_f32 v16, v16, v17
	v_cvt_pk_bf16_f32 v17, v18, v19
	v_cvt_pk_bf16_f32 v18, v12, v13
	v_cvt_pk_bf16_f32 v19, v14, v15
	s_add_u32 s100, s46, 0x58000
	s_addc_u32 s101, s47, 0
	global_store_dwordx4 v2, v[16:19], s[100:101] offset:0
	s_waitcnt vmcnt(6)
; __device__ __forceinline__ float sigmoid_f(float x) { return __builtin_amdgcn_rcpf(1.f + __builtin_amdgcn_exp2f(-1.4426950408889634f * x)); }
; __device__ __forceinline__ float bf_lo(unsigned u) { return __uint_as_float(u << 16); }
; __device__ __forceinline__ float bf_hi(unsigned u) { return __uint_as_float(u & 0xffff0000u); }
; __device__ __forceinline__ u32x4 pack8(const f32x4 v0, const f32x4 v1) { u32x4 w; w.x = cvt_pk_bf16(v0[0], v0[1]); w.y = cvt_pk_bf16(v0[2], v0[3]); w.z = cvt_pk_bf16(v1[0], v1[1]); w.w = cvt_pk_bf16(v1[2], v1[3]); return w; }
;     __device__ __forceinline__ void operator()(const f32x4 (&acc)[2][2][4][2], const Unit& u, int wr, int wc, int fr, int fq) const {
;     ...
;                     for (int bj = 0; bj < 2; ++bj) { f32x4 v0 = acc[ai][bj][m][0], v1 = acc[ai][bj][m][1]; bf16_t* p = ob + (unsigned)(r * ld + col0 + bj * HALF);
;                         if constexpr (MODE == 0) { v0 = v0 * sc; v1 = v1 * sc; }
;                         if constexpr (MODE == 3) { v0 = (v0 + bv[bj][0]) * sv[bj][0]; v1 = (v1 + bv[bj][1]) * sv[bj][1]; }
;                         if constexpr (MODE == 4) {
; #pragma unroll
;                             for (int e = 0; e < 4; ++e) { v0[e] = sigmoid_f(v0[e] * sc); v1[e] = sigmoid_f(v1[e] * sc); } }
;                         if constexpr (MODE == 5) { const u32x4 g = *(const u32x4*)(G + (unsigned)(r * ld + col0 + bj * HALF));
;                             v0 = v0 * (f32x4){bf_lo(g.x), bf_hi(g.x), bf_lo(g.y), bf_hi(g.y)}; v1 = v1 * (f32x4){bf_lo(g.z), bf_hi(g.z), bf_lo(g.w), bf_hi(g.w)};
;                             if (!first) { const u32x4 q = *(const u32x4*)p; v0 = v0 + (f32x4){bf_lo(q.x), bf_hi(q.x), bf_lo(q.y), bf_hi(q.y)}; v1 = v1 + (f32x4){bf_lo(q.z), bf_hi(q.z), bf_lo(q.w), bf_hi(q.w)}; } }
;                         *(u32x4*)p = pack8(v0, v1); }
	v_lshlrev_b32_e32 v220, 16, v152
	v_and_b32_e32 v221, 0xffff0000, v152
	v_pk_mul_f32 v[8:9], v[8:9], v[220:221]
	v_lshlrev_b32_e32 v222, 16, v153
	v_and_b32_e32 v223, 0xffff0000, v153
	v_pk_mul_f32 v[10:11], v[10:11], v[222:223]
	v_lshlrev_b32_e32 v224, 16, v154
	v_and_b32_e32 v225, 0xffff0000, v154
	v_pk_mul_f32 v[4:5], v[4:5], v[224:225]
	v_lshlrev_b32_e32 v226, 16, v155
	v_and_b32_e32 v227, 0xffff0000, v155
	v_pk_mul_f32 v[6:7], v[6:7], v[226:227]
	v_lshlrev_b32_e32 v220, 16, v156
	v_and_b32_e32 v221, 0xffff0000, v156
	v_pk_add_f32 v[8:9], v[8:9], v[220:221]
	v_lshlrev_b32_e32 v222, 16, v157
	v_and_b32_e32 v223, 0xffff0000, v157
	v_pk_add_f32 v[10:11], v[10:11], v[222:223]
	v_lshlrev_b32_e32 v224, 16, v158
	v_and_b32_e32 v225, 0xffff0000, v158
	v_pk_add_f32 v[4:5], v[4:5], v[224:225]
	v_lshlrev_b32_e32 v226, 16, v159
	v_and_b32_e32 v227, 0xffff0000, v159
	v_pk_add_f32 v[6:7], v[6:7], v[226:227]
	v_cvt_pk_bf16_f32 v8, v8, v9
	v_cvt_pk_bf16_f32 v9, v10, v11
	v_cvt_pk_bf16_f32 v10, v4, v5
	v_cvt_pk_bf16_f32 v11, v6, v7
	s_add_u32 s100, s46, 0x58000
	s_addc_u32 s101, s47, 0
	global_store_dwordx4 v2, v[8:11], s[100:101] offset:256
	s_branch .Le5_done
.Le5_first:
	s_add_u32 s98, s50, 0x0
	s_addc_u32 s99, s51, 0
	global_load_dwordx4 v[142:145], v2, s[98:99] offset:0
	s_add_u32 s98, s50, 0x0
	s_addc_u32 s99, s51, 0
	global_load_dwordx4 v[148:151], v2, s[98:99] offset:256
	s_add_u32 s98, s50, 0x8000
	s_addc_u32 s99, s51, 0
	global_load_dwordx4 v[152:155], v2, s[98:99] offset:0
	s_add_u32 s98, s50, 0x8000
	s_addc_u32 s99, s51, 0
	global_load_dwordx4 v[156:159], v2, s[98:99] offset:256
	s_add_u32 s98, s50, 0x10000
	s_addc_u32 s99, s51, 0
	global_load_dwordx4 v[160:163], v2, s[98:99] offset:0
	s_add_u32 s98, s50, 0x10000
	s_addc_u32 s99, s51, 0
	global_load_dwordx4 v[164:167], v2, s[98:99] offset:256
	s_add_u32 s98, s50, 0x18000
	s_addc_u32 s99, s51, 0
	global_load_dwordx4 v[168:171], v2, s[98:99] offset:0
	s_add_u32 s98, s50, 0x18000
	s_addc_u32 s99, s51, 0
	global_load_dwordx4 v[172:175], v2, s[98:99] offset:256
	s_add_u32 s98, s50, 0x40000
	s_addc_u32 s99, s51, 0
	global_load_dwordx4 v[176:179], v2, s[98:99] offset:0
	s_add_u32 s98, s50, 0x40000
	s_addc_u32 s99, s51, 0
	global_load_dwordx4 v[180:183], v2, s[98:99] offset:256
	s_add_u32 s98, s50, 0x48000
	s_addc_u32 s99, s51, 0
	global_load_dwordx4 v[194:197], v2, s[98:99] offset:0
	s_add_u32 s98, s50, 0x48000
	s_addc_u32 s99, s51, 0
	global_load_dwordx4 v[198:201], v2, s[98:99] offset:256
	s_add_u32 s98, s50, 0x50000
	s_addc_u32 s99, s51, 0
	global_load_dwordx4 v[202:205], v2, s[98:99] offset:0
	s_add_u32 s98, s50, 0x50000
	s_addc_u32 s99, s51, 0
	global_load_dwordx4 v[206:209], v2, s[98:99] offset:256
	s_waitcnt vmcnt(13)
	v_lshlrev_b32_e32 v220, 16, v142
	v_and_b32_e32 v221, 0xffff0000, v142
	v_pk_mul_f32 v[128:129], v[128:129], v[220:221]
	v_lshlrev_b32_e32 v222, 16, v143
	v_and_b32_e32 v223, 0xffff0000, v143
	v_pk_mul_f32 v[130:131], v[130:131], v[222:223]
	v_lshlrev_b32_e32 v224, 16, v144
	v_and_b32_e32 v225, 0xffff0000, v144
	v_pk_mul_f32 v[124:125], v[124:125], v[224:225]
	v_lshlrev_b32_e32 v226, 16, v145
	v_and_b32_e32 v227, 0xffff0000, v145
	v_pk_mul_f32 v[126:127], v[126:127], v[226:227]
	v_cvt_pk_bf16_f32 v128, v128, v129
	v_cvt_pk_bf16_f32 v129, v130, v131
	v_cvt_pk_bf16_f32 v130, v124, v125
	v_cvt_pk_bf16_f32 v131, v126, v127
	s_add_u32 s100, s46, 0x0
	s_addc_u32 s101, s47, 0
	global_store_dwordx4 v2, v[128:131], s[100:101] offset:0
	s_add_u32 s98, s50, 0x58000
	s_addc_u32 s99, s51, 0
	global_load_dwordx4 v[142:145], v2, s[98:99] offset:0
	s_waitcnt vmcnt(14)
	v_lshlrev_b32_e32 v220, 16, v148
	v_and_b32_e32 v221, 0xffff0000, v148
	v_pk_mul_f32 v[120:121], v[120:121], v[220:221]
	v_lshlrev_b32_e32 v222, 16, v149
	v_and_b32_e32 v223, 0xffff0000, v149
	v_pk_mul_f32 v[122:123], v[122:123], v[222:223]
	v_lshlrev_b32_e32 v224, 16, v150
	v_and_b32_e32 v225, 0xffff0000, v150
	v_pk_mul_f32 v[116:117], v[116:117], v[224:225]
	v_lshlrev_b32_e32 v226, 16, v151
	v_and_b32_e32 v227, 0xffff0000, v151
	v_pk_mul_f32 v[118:119], v[118:119], v[226:227]
	v_cvt_pk_bf16_f32 v120, v120, v121
	v_cvt_pk_bf16_f32 v121, v122, v123
	v_cvt_pk_bf16_f32 v122, v116, v117
	v_cvt_pk_bf16_f32 v123, v118, v119
	s_add_u32 s100, s46, 0x0
	s_addc_u32 s101, s47, 0
	global_store_dwordx4 v2, v[120:123], s[100:101] offset:256
	s_add_u32 s98, s50, 0x58000
	s_addc_u32 s99, s51, 0
	global_load_dwordx4 v[148:151], v2, s[98:99] offset:256
	s_waitcnt vmcnt(15)
	v_lshlrev_b32_e32 v220, 16, v152
	v_and_b32_e32 v221, 0xffff0000, v152
	v_pk_mul_f32 v[112:113], v[112:113], v[220:221]
	v_lshlrev_b32_e32 v222, 16, v153
	v_and_b32_e32 v223, 0xffff0000, v153
	v_pk_mul_f32 v[114:115], v[114:115], v[222:223]
	v_lshlrev_b32_e32 v224, 16, v154
	v_and_b32_e32 v225, 0xffff0000, v154
	v_pk_mul_f32 v[108:109], v[108:109], v[224:225]
	v_lshlrev_b32_e32 v226, 16, v155
	v_and_b32_e32 v227, 0xffff0000, v155
	v_pk_mul_f32 v[110:111], v[110:111], v[226:227]
	v_cvt_pk_bf16_f32 v112, v112, v113
	v_cvt_pk_bf16_f32 v113, v114, v115
	v_cvt_pk_bf16_f32 v114, v108, v109
	v_cvt_pk_bf16_f32 v115, v110, v111
	s_add_u32 s100, s46, 0x8000
	s_addc_u32 s101, s47, 0
	global_store_dwordx4 v2, v[112:115], s[100:101] offset:0
	s_waitcnt vmcnt(15)
	v_lshlrev_b32_e32 v220, 16, v156
	v_and_b32_e32 v221, 0xffff0000, v156
	v_pk_mul_f32 v[104:105], v[104:105], v[220:221]
	v_lshlrev_b32_e32 v222, 16, v157
	v_and_b32_e32 v223, 0xffff0000, v157
	v_pk_mul_f32 v[106:107], v[106:107], v[222:223]
	v_lshlrev_b32_e32 v224, 16, v158
	v_and_b32_e32 v225, 0xffff0000, v158
	v_pk_mul_f32 v[100:101], v[100:101], v[224:225]
	v_lshlrev_b32_e32 v226, 16, v159
	v_and_b32_e32 v227, 0xffff0000, v159
	v_pk_mul_f32 v[102:103], v[102:103], v[226:227]
	v_cvt_pk_bf16_f32 v104, v104, v105
	v_cvt_pk_bf16_f32 v105, v106, v107
	v_cvt_pk_bf16_f32 v106, v100, v101
	v_cvt_pk_bf16_f32 v107, v102, v103
	s_add_u32 s100, s46, 0x8000
	s_addc_u32 s101, s47, 0
	global_store_dwordx4 v2, v[104:107], s[100:101] offset:256
	s_waitcnt vmcnt(15)
; __device__ __forceinline__ float sigmoid_f(float x) { return __builtin_amdgcn_rcpf(1.f + __builtin_amdgcn_exp2f(-1.4426950408889634f * x)); }
; __device__ __forceinline__ float bf_lo(unsigned u) { return __uint_as_float(u << 16); }
; __device__ __forceinline__ float bf_hi(unsigned u) { return __uint_as_float(u & 0xffff0000u); }
; __device__ __forceinline__ u32x4 pack8(const f32x4 v0, const f32x4 v1) { u32x4 w; w.x = cvt_pk_bf16(v0[0], v0[1]); w.y = cvt_pk_bf16(v0[2], v0[3]); w.z = cvt_pk_bf16(v1[0], v1[1]); w.w = cvt_pk_bf16(v1[2], v1[3]); return w; }
;     __device__ __forceinline__ void operator()(const f32x4 (&acc)[2][2][4][2], const Unit& u, int wr, int wc, int fr, int fq) const {
;     ...
;                     for (int bj = 0; bj < 2; ++bj) { f32x4 v0 = acc[ai][bj][m][0], v1 = acc[ai][bj][m][1]; bf16_t* p = ob + (unsigned)(r * ld + col0 + bj * HALF);
;                         if constexpr (MODE == 0) { v0 = v0 * sc; v1 = v1 * sc; }
;                         if constexpr (MODE == 3) { v0 = (v0 + bv[bj][0]) * sv[bj][0]; v1 = (v1 + bv[bj][1]) * sv[bj][1]; }
;                         if constexpr (MODE == 4) {
; #pragma unroll
;                             for (int e = 0; e < 4; ++e) { v0[e] = sigmoid_f(v0[e] * sc); v1[e] = sigmoid_f(v1[e] * sc); } }
;                         if constexpr (MODE == 5) { const u32x4 g = *(const u32x4*)(G + (unsigned)(r * ld + col0 + bj * HALF));
;                             v0 = v0 * (f32x4){bf_lo(g.x), bf_hi(g.x), bf_lo(g.y), bf_hi(g.y)}; v1 = v1 * (f32x4){bf_lo(g.z), bf_hi(g.z), bf_lo(g.w), bf_hi(g.w)};
;                             if (!first) { const u32x4 q = *(const u32x4*)p; v0 = v0 + (f32x4){bf_lo(q.x), bf_hi(q.x), bf_lo(q.y), bf_hi(q.y)}; v1 = v1 + (f32x4){bf_lo(q.z), bf_hi(q.z), bf_lo(q.w), bf_hi(q.w)}; } }
;                         *(u32x4*)p = pack8(v0, v1); }
	v_lshlrev_b32_e32 v220, 16, v160
	v_and_b32_e32 v221, 0xffff0000, v160
	v_pk_mul_f32 v[96:97], v[96:97], v[220:221]
	v_lshlrev_b32_e32 v222, 16, v161
	v_and_b32_e32 v223, 0xffff0000, v161
	v_pk_mul_f32 v[98:99], v[98:99], v[222:223]
	v_lshlrev_b32_e32 v224, 16, v162
	v_and_b32_e32 v225, 0xffff0000, v162
	v_pk_mul_f32 v[92:93], v[92:93], v[224:225]
	v_lshlrev_b32_e32 v226, 16, v163
	v_and_b32_e32 v227, 0xffff0000, v163
	v_pk_mul_f32 v[94:95], v[94:95], v[226:227]
	v_cvt_pk_bf16_f32 v96, v96, v97
	v_cvt_pk_bf16_f32 v97, v98, v99
	v_cvt_pk_bf16_f32 v98, v92, v93
	v_cvt_pk_bf16_f32 v99, v94, v95
	s_add_u32 s100, s46, 0x10000
	s_addc_u32 s101, s47, 0
	global_store_dwordx4 v2, v[96:99], s[100:101] offset:0
	s_waitcnt vmcnt(15)
	v_lshlrev_b32_e32 v220, 16, v164
	v_and_b32_e32 v221, 0xffff0000, v164
	v_pk_mul_f32 v[88:89], v[88:89], v[220:221]
	v_lshlrev_b32_e32 v222, 16, v165
	v_and_b32_e32 v223, 0xffff0000, v165
	v_pk_mul_f32 v[90:91], v[90:91], v[222:223]
	v_lshlrev_b32_e32 v224, 16, v166
	v_and_b32_e32 v225, 0xffff0000, v166
	v_pk_mul_f32 v[84:85], v[84:85], v[224:225]
	v_lshlrev_b32_e32 v226, 16, v167
	v_and_b32_e32 v227, 0xffff0000, v167
	v_pk_mul_f32 v[86:87], v[86:87], v[226:227]
	v_cvt_pk_bf16_f32 v88, v88, v89
	v_cvt_pk_bf16_f32 v89, v90, v91
	v_cvt_pk_bf16_f32 v90, v84, v85
	v_cvt_pk_bf16_f32 v91, v86, v87
	s_add_u32 s100, s46, 0x10000
	s_addc_u32 s101, s47, 0
	global_store_dwordx4 v2, v[88:91], s[100:101] offset:256
	s_waitcnt vmcnt(15)
	v_lshlrev_b32_e32 v220, 16, v168
	v_and_b32_e32 v221, 0xffff0000, v168
	v_pk_mul_f32 v[80:81], v[80:81], v[220:221]
	v_lshlrev_b32_e32 v222, 16, v169
	v_and_b32_e32 v223, 0xffff0000, v169
	v_pk_mul_f32 v[82:83], v[82:83], v[222:223]
	v_lshlrev_b32_e32 v224, 16, v170
	v_and_b32_e32 v225, 0xffff0000, v170
	v_pk_mul_f32 v[76:77], v[76:77], v[224:225]
	v_lshlrev_b32_e32 v226, 16, v171
	v_and_b32_e32 v227, 0xffff0000, v171
	v_pk_mul_f32 v[78:79], v[78:79], v[226:227]
	v_cvt_pk_bf16_f32 v80, v80, v81
	v_cvt_pk_bf16_f32 v81, v82, v83
	v_cvt_pk_bf16_f32 v82, v76, v77
	v_cvt_pk_bf16_f32 v83, v78, v79
	s_add_u32 s100, s46, 0x18000
	s_addc_u32 s101, s47, 0
	global_store_dwordx4 v2, v[80:83], s[100:101] offset:0
	s_waitcnt vmcnt(15)
	v_lshlrev_b32_e32 v220, 16, v172
	v_and_b32_e32 v221, 0xffff0000, v172
	v_pk_mul_f32 v[72:73], v[72:73], v[220:221]
	v_lshlrev_b32_e32 v222, 16, v173
	v_and_b32_e32 v223, 0xffff0000, v173
	v_pk_mul_f32 v[74:75], v[74:75], v[222:223]
	v_lshlrev_b32_e32 v224, 16, v174
	v_and_b32_e32 v225, 0xffff0000, v174
	v_pk_mul_f32 v[68:69], v[68:69], v[224:225]
	v_lshlrev_b32_e32 v226, 16, v175
	v_and_b32_e32 v227, 0xffff0000, v175
	v_pk_mul_f32 v[70:71], v[70:71], v[226:227]
	v_cvt_pk_bf16_f32 v72, v72, v73
	v_cvt_pk_bf16_f32 v73, v74, v75
	v_cvt_pk_bf16_f32 v74, v68, v69
	v_cvt_pk_bf16_f32 v75, v70, v71
	s_add_u32 s100, s46, 0x18000
	s_addc_u32 s101, s47, 0
	global_store_dwordx4 v2, v[72:75], s[100:101] offset:256
	s_waitcnt vmcnt(15)
	v_lshlrev_b32_e32 v220, 16, v176
	v_and_b32_e32 v221, 0xffff0000, v176
	v_pk_mul_f32 v[64:65], v[64:65], v[220:221]
	v_lshlrev_b32_e32 v222, 16, v177
	v_and_b32_e32 v223, 0xffff0000, v177
	v_pk_mul_f32 v[66:67], v[66:67], v[222:223]
	v_lshlrev_b32_e32 v224, 16, v178
	v_and_b32_e32 v225, 0xffff0000, v178
	v_pk_mul_f32 v[60:61], v[60:61], v[224:225]
	v_lshlrev_b32_e32 v226, 16, v179
	v_and_b32_e32 v227, 0xffff0000, v179
	v_pk_mul_f32 v[62:63], v[62:63], v[226:227]
	v_cvt_pk_bf16_f32 v64, v64, v65
	v_cvt_pk_bf16_f32 v65, v66, v67
	v_cvt_pk_bf16_f32 v66, v60, v61
	v_cvt_pk_bf16_f32 v67, v62, v63
	s_add_u32 s100, s46, 0x40000
	s_addc_u32 s101, s47, 0
	global_store_dwordx4 v2, v[64:67], s[100:101] offset:0
	s_waitcnt vmcnt(15)
	v_lshlrev_b32_e32 v220, 16, v180
	v_and_b32_e32 v221, 0xffff0000, v180
	v_pk_mul_f32 v[56:57], v[56:57], v[220:221]
	v_lshlrev_b32_e32 v222, 16, v181
	v_and_b32_e32 v223, 0xffff0000, v181
	v_pk_mul_f32 v[58:59], v[58:59], v[222:223]
	v_lshlrev_b32_e32 v224, 16, v182
	v_and_b32_e32 v225, 0xffff0000, v182
	v_pk_mul_f32 v[52:53], v[52:53], v[224:225]
	v_lshlrev_b32_e32 v226, 16, v183
	v_and_b32_e32 v227, 0xffff0000, v183
	v_pk_mul_f32 v[54:55], v[54:55], v[226:227]
	v_cvt_pk_bf16_f32 v56, v56, v57
	v_cvt_pk_bf16_f32 v57, v58, v59
	v_cvt_pk_bf16_f32 v58, v52, v53
	v_cvt_pk_bf16_f32 v59, v54, v55
	s_add_u32 s100, s46, 0x40000
	s_addc_u32 s101, s47, 0
	global_store_dwordx4 v2, v[56:59], s[100:101] offset:256
	s_waitcnt vmcnt(15)
; __device__ __forceinline__ float sigmoid_f(float x) { return __builtin_amdgcn_rcpf(1.f + __builtin_amdgcn_exp2f(-1.4426950408889634f * x)); }
; __device__ __forceinline__ float bf_lo(unsigned u) { return __uint_as_float(u << 16); }
; __device__ __forceinline__ float bf_hi(unsigned u) { return __uint_as_float(u & 0xffff0000u); }
; #define PG8_BAR __builtin_amdgcn_s_barrier()
;     __device__ __forceinline__ void operator()(const f32x4 (&acc)[2][2][4][2], const Unit& u, int wr, int wc, int fr, int fq) const {
;     ...
;                     for (int bj = 0; bj < 2; ++bj) { f32x4 v0 = acc[ai][bj][m][0], v1 = acc[ai][bj][m][1]; bf16_t* p = ob + (unsigned)(r * ld + col0 + bj * HALF);
;                         if constexpr (MODE == 0) { v0 = v0 * sc; v1 = v1 * sc; }
;                         if constexpr (MODE == 3) { v0 = (v0 + bv[bj][0]) * sv[bj][0]; v1 = (v1 + bv[bj][1]) * sv[bj][1]; }
;                         if constexpr (MODE == 4) {
; #pragma unroll
;                             for (int e = 0; e < 4; ++e) { v0[e] = sigmoid_f(v0[e] * sc); v1[e] = sigmoid_f(v1[e] * sc); } }
;                         if constexpr (MODE == 5) { const u32x4 g = *(const u32x4*)(G + (unsigned)(r * ld + col0 + bj * HALF));
;                             v0 = v0 * (f32x4){bf_lo(g.x), bf_hi(g.x), bf_lo(g.y), bf_hi(g.y)}; v1 = v1 * (f32x4){bf_lo(g.z), bf_hi(g.z), bf_lo(g.w), bf_hi(g.w)};
;                             if (!first) { const u32x4 q = *(const u32x4*)p; v0 = v0 + (f32x4){bf_lo(q.x), bf_hi(q.x), bf_lo(q.y), bf_hi(q.y)}; v1 = v1 + (f32x4){bf_lo(q.z), bf_hi(q.z), bf_lo(q.w), bf_hi(q.w)}; } }
;                         *(u32x4*)p = pack8(v0, v1); }
; template <class Epi, class Sched, bool ALIGN_EPI = false, bool SP2 = false>
; __device__ __forceinline__ void gemm_phase(PG8_LAS unsigned char* lds, const Gemm g, const Sched& S, const Epi& E) {
;     ...
;         if (!has_next) break;
; #pragma unroll
;         for (int a = 0; a < 2; ++a)
; #pragma unroll
;             for (int b = 0; b < 2; ++b)
; #pragma unroll
;                 for (int m = 0; m < 4; ++m)
; #pragma unroll
;                     for (int n = 0; n < 2; ++n) acc[a][b][m][n] = (f32x4){0.f, 0.f, 0.f, 0.f};
;         cur = nxt; cA = nA; cB = nB; ++ui;
;         if constexpr (ALIGN_EPI) { if (wr == 1) PG8_BAR; }
	v_lshlrev_b32_e32 v220, 16, v194
	v_and_b32_e32 v221, 0xffff0000, v194
	v_pk_mul_f32 v[48:49], v[48:49], v[220:221]
	v_lshlrev_b32_e32 v222, 16, v195
	v_and_b32_e32 v223, 0xffff0000, v195
	v_pk_mul_f32 v[50:51], v[50:51], v[222:223]
	v_lshlrev_b32_e32 v224, 16, v196
	v_and_b32_e32 v225, 0xffff0000, v196
	v_pk_mul_f32 v[44:45], v[44:45], v[224:225]
	v_lshlrev_b32_e32 v226, 16, v197
	v_and_b32_e32 v227, 0xffff0000, v197
	v_pk_mul_f32 v[46:47], v[46:47], v[226:227]
	v_cvt_pk_bf16_f32 v48, v48, v49
	v_cvt_pk_bf16_f32 v49, v50, v51
	v_cvt_pk_bf16_f32 v50, v44, v45
	v_cvt_pk_bf16_f32 v51, v46, v47
	s_add_u32 s100, s46, 0x48000
	s_addc_u32 s101, s47, 0
	global_store_dwordx4 v2, v[48:51], s[100:101] offset:0
	s_waitcnt vmcnt(15)
	v_lshlrev_b32_e32 v220, 16, v198
	v_and_b32_e32 v221, 0xffff0000, v198
	v_pk_mul_f32 v[40:41], v[40:41], v[220:221]
	v_lshlrev_b32_e32 v222, 16, v199
	v_and_b32_e32 v223, 0xffff0000, v199
	v_pk_mul_f32 v[42:43], v[42:43], v[222:223]
	v_lshlrev_b32_e32 v224, 16, v200
	v_and_b32_e32 v225, 0xffff0000, v200
	v_pk_mul_f32 v[36:37], v[36:37], v[224:225]
	v_lshlrev_b32_e32 v226, 16, v201
	v_and_b32_e32 v227, 0xffff0000, v201
	v_pk_mul_f32 v[38:39], v[38:39], v[226:227]
	v_cvt_pk_bf16_f32 v40, v40, v41
	v_cvt_pk_bf16_f32 v41, v42, v43
	v_cvt_pk_bf16_f32 v42, v36, v37
	v_cvt_pk_bf16_f32 v43, v38, v39
	s_add_u32 s100, s46, 0x48000
	s_addc_u32 s101, s47, 0
	global_store_dwordx4 v2, v[40:43], s[100:101] offset:256
	s_waitcnt vmcnt(15)
	v_lshlrev_b32_e32 v220, 16, v202
	v_and_b32_e32 v221, 0xffff0000, v202
	v_pk_mul_f32 v[32:33], v[32:33], v[220:221]
	v_lshlrev_b32_e32 v222, 16, v203
	v_and_b32_e32 v223, 0xffff0000, v203
	v_pk_mul_f32 v[34:35], v[34:35], v[222:223]
	v_lshlrev_b32_e32 v224, 16, v204
	v_and_b32_e32 v225, 0xffff0000, v204
	v_pk_mul_f32 v[28:29], v[28:29], v[224:225]
	v_lshlrev_b32_e32 v226, 16, v205
	v_and_b32_e32 v227, 0xffff0000, v205
	v_pk_mul_f32 v[30:31], v[30:31], v[226:227]
	v_cvt_pk_bf16_f32 v32, v32, v33
	v_cvt_pk_bf16_f32 v33, v34, v35
	v_cvt_pk_bf16_f32 v34, v28, v29
	v_cvt_pk_bf16_f32 v35, v30, v31
	s_add_u32 s100, s46, 0x50000
	s_addc_u32 s101, s47, 0
	global_store_dwordx4 v2, v[32:35], s[100:101] offset:0
	s_waitcnt vmcnt(15)
	v_lshlrev_b32_e32 v220, 16, v206
	v_and_b32_e32 v221, 0xffff0000, v206
	v_pk_mul_f32 v[24:25], v[24:25], v[220:221]
	v_lshlrev_b32_e32 v222, 16, v207
	v_and_b32_e32 v223, 0xffff0000, v207
	v_pk_mul_f32 v[26:27], v[26:27], v[222:223]
	v_lshlrev_b32_e32 v224, 16, v208
	v_and_b32_e32 v225, 0xffff0000, v208
	v_pk_mul_f32 v[20:21], v[20:21], v[224:225]
	v_lshlrev_b32_e32 v226, 16, v209
	v_and_b32_e32 v227, 0xffff0000, v209
	v_pk_mul_f32 v[22:23], v[22:23], v[226:227]
	v_cvt_pk_bf16_f32 v24, v24, v25
	v_cvt_pk_bf16_f32 v25, v26, v27
	v_cvt_pk_bf16_f32 v26, v20, v21
	v_cvt_pk_bf16_f32 v27, v22, v23
	s_add_u32 s100, s46, 0x50000
	s_addc_u32 s101, s47, 0
	global_store_dwordx4 v2, v[24:27], s[100:101] offset:256
	s_waitcnt vmcnt(14)
	v_lshlrev_b32_e32 v220, 16, v142
	v_and_b32_e32 v221, 0xffff0000, v142
	v_pk_mul_f32 v[16:17], v[16:17], v[220:221]
	v_lshlrev_b32_e32 v222, 16, v143
	v_and_b32_e32 v223, 0xffff0000, v143
	v_pk_mul_f32 v[18:19], v[18:19], v[222:223]
	v_lshlrev_b32_e32 v224, 16, v144
	v_and_b32_e32 v225, 0xffff0000, v144
	v_pk_mul_f32 v[12:13], v[12:13], v[224:225]
	v_lshlrev_b32_e32 v226, 16, v145
	v_and_b32_e32 v227, 0xffff0000, v145
	v_pk_mul_f32 v[14:15], v[14:15], v[226:227]
	v_cvt_pk_bf16_f32 v16, v16, v17
	v_cvt_pk_bf16_f32 v17, v18, v19
	v_cvt_pk_bf16_f32 v18, v12, v13
	v_cvt_pk_bf16_f32 v19, v14, v15
	s_add_u32 s100, s46, 0x58000
	s_addc_u32 s101, s47, 0
	global_store_dwordx4 v2, v[16:19], s[100:101] offset:0
	s_waitcnt vmcnt(13)
	v_lshlrev_b32_e32 v220, 16, v148
	v_and_b32_e32 v221, 0xffff0000, v148
	v_pk_mul_f32 v[8:9], v[8:9], v[220:221]
	v_lshlrev_b32_e32 v222, 16, v149
	v_and_b32_e32 v223, 0xffff0000, v149
	v_pk_mul_f32 v[10:11], v[10:11], v[222:223]
	v_lshlrev_b32_e32 v224, 16, v150
	v_and_b32_e32 v225, 0xffff0000, v150
	v_pk_mul_f32 v[4:5], v[4:5], v[224:225]
	v_lshlrev_b32_e32 v226, 16, v151
	v_and_b32_e32 v227, 0xffff0000, v151
	v_pk_mul_f32 v[6:7], v[6:7], v[226:227]
	v_cvt_pk_bf16_f32 v8, v8, v9
	v_cvt_pk_bf16_f32 v9, v10, v11
	v_cvt_pk_bf16_f32 v10, v4, v5
	v_cvt_pk_bf16_f32 v11, v6, v7
	s_add_u32 s100, s46, 0x58000
	s_addc_u32 s101, s47, 0
	global_store_dwordx4 v2, v[8:11], s[100:101] offset:256
.Le5_done:
	s_and_b64 vcc, exec, s[40:41]
	s_mov_b64 s[40:41], -1
	s_cbranch_vccnz .LBB0_92
	s_andn2_b64 vcc, exec, s[62:63]
	s_cbranch_vccnz .LBB0_91
	s_barrier
	s_branch .LBB0_91

; #define LAS __attribute__((address_space(3)))
; __global__ void __launch_bounds__(NTHR) fwd_kernel(Args args) {
;     extern __shared__ __attribute__((aligned(16))) unsigned char lds_raw[];
;     LAS unsigned char* lds = (LAS unsigned char*)lds_raw;
	.amdhsa_kernel _Z10fwd_kernel4Args
		.amdhsa_group_segment_fixed_size 256
		.amdhsa_private_segment_fixed_size 0
		.amdhsa_kernarg_size 2616
		.amdhsa_user_sgpr_count 2
		.amdhsa_user_sgpr_dispatch_ptr 0
		.amdhsa_user_sgpr_queue_ptr 0
		.amdhsa_user_sgpr_kernarg_segment_ptr 1
		.amdhsa_user_sgpr_dispatch_id 0
		.amdhsa_user_sgpr_kernarg_preload_length 0
		.amdhsa_user_sgpr_kernarg_preload_offset 0
		.amdhsa_user_sgpr_private_segment_size 0
		.amdhsa_uses_dynamic_stack 0
		.amdhsa_enable_private_segment 0
		.amdhsa_system_sgpr_workgroup_id_x 1
		.amdhsa_system_sgpr_workgroup_id_y 0
		.amdhsa_system_sgpr_workgroup_id_z 0
		.amdhsa_system_sgpr_workgroup_info 0
		.amdhsa_system_vgpr_workitem_id 2
		.amdhsa_next_free_vgpr 256
		.amdhsa_next_free_sgpr 102
		.amdhsa_accum_offset 256
		.amdhsa_reserve_vcc 1
		.amdhsa_float_round_mode_32 0
		.amdhsa_float_round_mode_16_64 0
		.amdhsa_float_denorm_mode_32 3
		.amdhsa_float_denorm_mode_16_64 3
		.amdhsa_dx10_clamp 1
		.amdhsa_ieee_mode 1
		.amdhsa_fp16_overflow 0
		.amdhsa_tg_split 0
		.amdhsa_exception_fp_ieee_invalid_op 0
		.amdhsa_exception_fp_denorm_src 0
		.amdhsa_exception_fp_ieee_div_zero 0
		.amdhsa_exception_fp_ieee_overflow 0
		.amdhsa_exception_fp_ieee_underflow 0
		.amdhsa_exception_fp_ieee_inexact 0
		.amdhsa_exception_int_div_zero 0
	.end_amdhsa_kernel

; #define LAS __attribute__((address_space(3)))
; __global__ void __launch_bounds__(NTHR) fwd_kernel(Args args) {
;     extern __shared__ __attribute__((aligned(16))) unsigned char lds_raw[];
;     LAS unsigned char* lds = (LAS unsigned char*)lds_raw;
amdhsa.kernels:
  - .agpr_count:     0
    .args:
      - .offset:         0
        .size:           2360
        .value_kind:     by_value
      - .offset:         2360
        .size:           4
        .value_kind:     hidden_block_count_x
      - .offset:         2364
        .size:           4
        .value_kind:     hidden_block_count_y
      - .offset:         2368
        .size:           4
        .value_kind:     hidden_block_count_z
      - .offset:         2372
        .size:           2
        .value_kind:     hidden_group_size_x
      - .offset:         2374
        .size:           2
        .value_kind:     hidden_group_size_y
      - .offset:         2376
        .size:           2
        .value_kind:     hidden_group_size_z
      - .offset:         2378
        .size:           2
        .value_kind:     hidden_remainder_x
      - .offset:         2380
        .size:           2
        .value_kind:     hidden_remainder_y
      - .offset:         2382
        .size:           2
        .value_kind:     hidden_remainder_z
      - .offset:         2400
        .size:           8
        .value_kind:     hidden_global_offset_x
      - .offset:         2408
        .size:           8
        .value_kind:     hidden_global_offset_y
      - .offset:         2416
        .size:           8
        .value_kind:     hidden_global_offset_z
      - .offset:         2424
        .size:           2
        .value_kind:     hidden_grid_dims
      - .offset:         2448
        .size:           8
        .value_kind:     hidden_multigrid_sync_arg
      - .offset:         2480
        .size:           4
        .value_kind:     hidden_dynamic_lds_size
    .group_segment_fixed_size: 256
    .kernarg_segment_align: 8
    .kernarg_segment_size: 2616
    .language:       OpenCL C
    .language_version:
      - 2
      - 0
    .max_flat_workgroup_size: 512
    .name:           _Z10fwd_kernel4Args
    .private_segment_fixed_size: 0
    .sgpr_count:     108
    .sgpr_spill_count: 103
    .symbol:         _Z10fwd_kernel4Args.kd
    .uniform_work_group_size: 1
    .uses_dynamic_stack: false
    .vgpr_count:     256
    .vgpr_spill_count: 0
    .wavefront_size: 64
